# mLSTM chunk_out V staging: four V loads issued together with counted vmcnt waits instead of load-wait(0)-write per load
# speedup vs baseline: 1.0022x; 1.0022x over previous
; #define LAS __attribute__((address_space(3)))
; __device__ __forceinline__ void unpack8(const u32x4 w, float (&o)[8]) { o[0] = bflo(w.x); o[1] = bfhi(w.x); o[2] = bflo(w.y); o[3] = bfhi(w.y); o[4] = bflo(w.z); o[5] = bfhi(w.z); o[6] = bflo(w.w); o[7] = bfhi(w.w); }
; __device__ __forceinline__ u32x4 pack8(const float (&o)[8]) { return (u32x4){pk2(o[0], o[1]), pk2(o[2], o[3]), pk2(o[4], o[5]), pk2(o[6], o[7])}; }
; __device__ __forceinline__ void stage_vt(LAS unsigned char* lds, const bf16_t* P, int c, int h, int wid, int lane) {
;   LAS bf16_t* VT = (LAS bf16_t*)(lds + C_VT);
;   u32x4 vv[4];
; #pragma unroll
;   for (int g = 0; g < 4; ++g) vv[g] = *(const u32x4*)(P + (size_t)(c * 64 + lane) * 3328 + 1024 + h * 256 + 8 * (4 * wid + g));
; #pragma unroll
;   for (int g = 0; g < 4; ++g) { const unsigned w[4] = {vv[g].x, vv[g].y, vv[g].z, vv[g].w}; const int v0 = 8 * (4 * wid + g);
; #pragma unroll
;     for (int e = 0; e < 4; ++e) { VT[(v0 + 2 * e) * 72 + lane] = (bf16_t)(w[e] & 0xffffu); VT[(v0 + 2 * e + 1) * 72 + lane] = (bf16_t)(w[e] >> 16); } }
; }
; template <bool IS_ML>
; __device__ __forceinline__ void chunk_out(LAS unsigned char* lds, unsigned char* ws, const float* w1, const float* w2, const float* onorm, int bid, int nb, int wid_s) {
;     ...
;       u32x4 qv[2], kv[2];
; #pragma unroll
;       for (int g = 0; g < 2; ++g) { const bf16_t* rp = P + (size_t)(c * 64 + lane) * 3328 + h * 128 + 8 * (2 * wid + g); qv[g] = *(const u32x4*)rp; kv[g] = *(const u32x4*)(rp + 512); }
;       stage_vt(lds, P, c, h, wid, lane);
; #pragma unroll
;       for (int g = 0; g < 2; ++g) { const int d0 = 8 * (2 * wid + g); float q8[8], k8[8]; unpack8(qv[g], q8); unpack8(kv[g], k8);
;         if (IS_ML) { for (int e = 0; e < 8; ++e) k8[e] *= QSCALE; }
;         else { const f32x4 ca = *(const LAS f32x4*)(CUM + lane * CS + d0), cb = *(const LAS f32x4*)(CUM + lane * CS + d0 + 4); const float cu[8] = {ca.x, ca.y, ca.z, ca.w, cb.x, cb.y, cb.z, cb.w};
; #pragma unroll
;           for (int e = 0; e < 8; ++e) { const float ex = __expf(cu[e]); q8[e] *= ex * QSCALE; k8[e] *= __builtin_amdgcn_rcpf(ex); } }
;         *(LAS u32x4*)(lds + C_QD + (lane * 136 + d0) * 2) = pack8(q8); *(LAS u32x4*)(lds + C_KI + (lane * 136 + d0) * 2) = pack8(k8); }
;     }
;     __syncthreads();
.LBB0_155:
	s_or_b64 exec, exec, s[54:55]
	s_lshl_b32 s54, s48, 6
	v_or_b32_e32 v6, s54, v133
	v_mov_b64_e32 v[4:5], s[96:97]
	s_movk_i32 s30, 0x1a00
	v_mad_i64_i32 v[20:21], s[30:31], v6, s30, v[4:5]
	s_lshl_b32 s58, s87, 8
	s_lshl_b32 s30, s87, 9
	s_mov_b32 s31, s59
	v_lshl_add_u64 v[4:5], v[20:21], 0, s[58:59]
	v_lshl_add_u64 v[20:21], v[20:21], 0, s[30:31]
	v_lshl_add_u64 v[12:13], v[108:109], 1, v[4:5]
	v_lshl_add_u64 v[24:25], v[110:111], 1, v[20:21]
	s_waitcnt lgkmcnt(0)
	s_barrier
	global_load_dwordx4 v[8:11], v[12:13], off offset:16
	global_load_dwordx4 v[16:19], v[12:13], off
	global_load_dwordx4 v[4:7], v[12:13], off offset:1040
	s_nop 0
	global_load_dwordx4 v[12:15], v[12:13], off offset:1024
	s_mov_b32 s30, 0x3db504f3
	global_load_dwordx4 v[20:23], v[24:25], off offset:2048
	global_load_dwordx4 v[244:247], v[24:25], off offset:2064
	global_load_dwordx4 v[248:251], v[24:25], off offset:2080
	s_nop 0
	global_load_dwordx4 v[24:27], v[24:25], off offset:2096
	s_waitcnt vmcnt(3)
	ds_write_b16 v139, v20
	ds_write_b16_d16_hi v139, v20 offset:144
	ds_write_b16 v139, v21 offset:288
	ds_write_b16_d16_hi v139, v21 offset:432
	ds_write_b16 v139, v22 offset:576
	ds_write_b16_d16_hi v139, v22 offset:720
	ds_write_b16 v139, v23 offset:864
	ds_write_b16_d16_hi v139, v23 offset:1008
	s_waitcnt vmcnt(2)
	ds_write_b16 v140, v244
	ds_write_b16_d16_hi v140, v244 offset:144
	ds_write_b16 v139, v245 offset:1440
	ds_write_b16_d16_hi v139, v245 offset:1584
	ds_write_b16 v139, v246 offset:1728
	ds_write_b16_d16_hi v139, v246 offset:1872
	ds_write_b16 v139, v247 offset:2016
	ds_write_b16_d16_hi v139, v247 offset:2160
	s_waitcnt vmcnt(1)
	ds_write_b16 v141, v248
	ds_write_b16_d16_hi v141, v248 offset:144
	ds_write_b16 v139, v249 offset:2592
	ds_write_b16_d16_hi v139, v249 offset:2736
	ds_write_b16 v139, v250 offset:2880
	ds_write_b16_d16_hi v139, v250 offset:3024
	ds_write_b16 v139, v251 offset:3168
	ds_write_b16_d16_hi v139, v251 offset:3312
	s_waitcnt vmcnt(0)
	ds_write_b16 v142, v24
	ds_write_b16_d16_hi v142, v24 offset:144
	ds_write_b16 v139, v25 offset:3744
	ds_write_b16_d16_hi v139, v25 offset:3888
	ds_write_b16 v139, v26 offset:4032
	ds_write_b16_d16_hi v139, v26 offset:4176
	ds_write_b16 v139, v27 offset:4320
	ds_write_b16_d16_hi v139, v27 offset:4464
	ds_write_b128 v225, v[16:19] offset:33792
	v_lshlrev_b32_e32 v17, 16, v13
	v_lshlrev_b32_e32 v16, 16, v12
	v_and_b32_e32 v13, 0xffff0000, v13
	v_and_b32_e32 v12, 0xffff0000, v12
	v_lshlrev_b32_e32 v19, 16, v15
	v_lshlrev_b32_e32 v18, 16, v14
	v_and_b32_e32 v15, 0xffff0000, v15
	v_and_b32_e32 v14, 0xffff0000, v14
	v_pk_mul_f32 v[12:13], v[12:13], s[30:31] op_sel_hi:[1,0]
	v_pk_mul_f32 v[14:15], v[14:15], s[30:31] op_sel_hi:[1,0]
	v_pk_mul_f32 v[16:17], v[16:17], s[30:31] op_sel_hi:[1,0]
	v_pk_mul_f32 v[18:19], v[18:19], s[30:31] op_sel_hi:[1,0]
	v_bfe_u32 v20, v15, 16, 1
	v_bfe_u32 v21, v14, 16, 1
	v_bfe_u32 v22, v13, 16, 1
	v_bfe_u32 v23, v12, 16, 1
	v_add3_u32 v12, v12, v23, s65
	v_add3_u32 v13, v13, v22, s65
	v_add3_u32 v14, v14, v21, s65
	v_add3_u32 v15, v15, v20, s65
	v_bfe_u32 v20, v16, 16, 1
	v_bfe_u32 v21, v17, 16, 1
	v_bfe_u32 v22, v18, 16, 1
	v_bfe_u32 v23, v19, 16, 1
	v_add3_u32 v19, v19, v23, s65
	v_add3_u32 v18, v18, v22, s65
	v_add3_u32 v17, v17, v21, s65
	v_add3_u32 v16, v16, v20, s65
	v_lshrrev_b32_e32 v16, 16, v16
	v_lshrrev_b32_e32 v17, 16, v17
	v_lshrrev_b32_e32 v18, 16, v18
	v_lshrrev_b32_e32 v19, 16, v19
	v_and_or_b32 v15, v15, s53, v19
	v_and_or_b32 v14, v14, s53, v18
	v_and_or_b32 v13, v13, s53, v17
	v_and_or_b32 v12, v12, s53, v16
	ds_write_b128 v225, v[12:15] offset:51200
	ds_write_b128 v225, v[8:11] offset:33808
	v_lshlrev_b32_e32 v9, 16, v5
	v_lshlrev_b32_e32 v8, 16, v4
	v_and_b32_e32 v5, 0xffff0000, v5
	v_and_b32_e32 v4, 0xffff0000, v4
	v_lshlrev_b32_e32 v11, 16, v7
	v_lshlrev_b32_e32 v10, 16, v6
	v_and_b32_e32 v7, 0xffff0000, v7
	v_and_b32_e32 v6, 0xffff0000, v6
	v_pk_mul_f32 v[4:5], v[4:5], s[30:31] op_sel_hi:[1,0]
	v_pk_mul_f32 v[6:7], v[6:7], s[30:31] op_sel_hi:[1,0]
	v_pk_mul_f32 v[8:9], v[8:9], s[30:31] op_sel_hi:[1,0]
	v_pk_mul_f32 v[10:11], v[10:11], s[30:31] op_sel_hi:[1,0]
	v_bfe_u32 v12, v7, 16, 1
	v_bfe_u32 v13, v6, 16, 1
	v_bfe_u32 v14, v5, 16, 1
	v_bfe_u32 v15, v4, 16, 1
	v_add3_u32 v4, v4, v15, s65
	v_add3_u32 v5, v5, v14, s65
	v_add3_u32 v6, v6, v13, s65
	v_add3_u32 v7, v7, v12, s65
	v_bfe_u32 v12, v8, 16, 1
	v_bfe_u32 v13, v9, 16, 1
	v_bfe_u32 v14, v10, 16, 1
	v_bfe_u32 v15, v11, 16, 1
	v_add3_u32 v11, v11, v15, s65
	v_add3_u32 v10, v10, v14, s65
	v_add3_u32 v9, v9, v13, s65
	v_add3_u32 v8, v8, v12, s65
	s_lshl_b32 s30, s88, 7
	v_lshrrev_b32_e32 v8, 16, v8
	v_lshrrev_b32_e32 v9, 16, v9
	v_lshrrev_b32_e32 v10, 16, v10
	v_lshrrev_b32_e32 v11, 16, v11
	s_ashr_i32 s31, s30, 31
	v_and_or_b32 v7, v7, s53, v11
	v_and_or_b32 v6, v6, s53, v10
	v_and_or_b32 v5, v5, s53, v9
	v_and_or_b32 v4, v4, s53, v8
	v_lshl_add_u64 v[8:9], s[30:31], 2, v[114:115]
	ds_write_b128 v225, v[4:7] offset:51216
	s_waitcnt lgkmcnt(0)
	s_barrier
; template <int MASK> __device__ __forceinline__ float sx(float v) { return __builtin_bit_cast(float, __builtin_amdgcn_ds_swizzle(__builtin_bit_cast(int, v), (MASK << 10) | 0x1f)); }
; __device__ __forceinline__ f32x4 mfma16(bf16x8 a, bf16x8 b, f32x4 c) { return __builtin_amdgcn_mfma_f32_16x16x32_bf16(a, b, c, 0, 0, 0); }
; template <bool IS_ML>
; __device__ __forceinline__ void chunk_out(LAS unsigned char* lds, unsigned char* ws, const float* w1, const float* w2, const float* onorm, int bid, int nb, int wid_s) {
;     ...
;     float dinter = 0.f;
;     if (IS_ML) {
;       const int t = tid >> 3, part = tid & 7; const float* NST = (const float*)(ws + WS_SMALL + SM_NST) + (c * 4 + h) * 128;
;       float s = 0.f; for (int j = 0; j < 16; ++j) { const int d = part * 16 + j; s += bf2f(QD[t * 136 + d]) * NST[d]; }
;       s += sx<1>(s); s += sx<2>(s); s += sx<4>(s); dinter = s;
;     }
;     { const int tt = wid >> 1;
; #pragma unroll
;       for (int q = 0; q < 2; ++q) { const int st = 2 * (wid & 1) + q; f32x4 sc = (f32x4){0.f, 0.f, 0.f, 0.f};
;         if (st <= tt) {
; #pragma unroll
;           for (int ks = 0; ks < 4; ++ks) sc = mfma16(LDSV8(C_QD + ((tt * 16 + fr) * 136 + ks * 32 + kg * 8) * 2), LDSV8(C_KI + ((st * 16 + fr) * 136 + ks * 32 + kg * 8) * 2), sc);
;         }
	ds_read_b128 v[4:7], v148 offset:33792
	ds_read_b128 v[10:13], v148 offset:33808
	global_load_dwordx4 v[14:17], v[8:9], off offset:48
	global_load_dwordx4 v[18:21], v[8:9], off offset:32
	global_load_dwordx4 v[22:25], v[8:9], off offset:16
	global_load_dwordx4 v[26:29], v[8:9], off
	v_mov_b32_e32 v8, 0
	s_waitcnt lgkmcnt(1)
	v_lshlrev_b32_e32 v30, 16, v4
	v_and_b32_e32 v4, 0xffff0000, v4
	s_waitcnt vmcnt(0)
	v_fma_f32 v9, v26, v30, 0
	v_fmac_f32_e32 v9, v27, v4
	v_lshlrev_b32_e32 v4, 16, v5
	v_fmac_f32_e32 v9, v28, v4
	v_and_b32_e32 v4, 0xffff0000, v5
	v_fmac_f32_e32 v9, v29, v4
	v_lshlrev_b32_e32 v4, 16, v6
	v_fmac_f32_e32 v9, v22, v4
	v_and_b32_e32 v4, 0xffff0000, v6
	v_fmac_f32_e32 v9, v23, v4
	v_lshlrev_b32_e32 v4, 16, v7
	v_fmac_f32_e32 v9, v24, v4
	v_and_b32_e32 v4, 0xffff0000, v7
	v_fmac_f32_e32 v9, v25, v4
	s_waitcnt lgkmcnt(0)
	v_lshlrev_b32_e32 v4, 16, v10
	v_fmac_f32_e32 v9, v18, v4
	v_and_b32_e32 v4, 0xffff0000, v10
	v_fmac_f32_e32 v9, v19, v4
	v_lshlrev_b32_e32 v4, 16, v11
	v_fmac_f32_e32 v9, v20, v4
	v_and_b32_e32 v4, 0xffff0000, v11
	v_fmac_f32_e32 v9, v21, v4
	v_lshlrev_b32_e32 v4, 16, v12
	v_fmac_f32_e32 v9, v14, v4
	v_and_b32_e32 v4, 0xffff0000, v12
	v_fmac_f32_e32 v9, v15, v4
	v_lshlrev_b32_e32 v4, 16, v13
	v_fmac_f32_e32 v9, v16, v4
	v_and_b32_e32 v4, 0xffff0000, v13
	v_fmac_f32_e32 v9, v17, v4
	ds_swizzle_b32 v4, v9 offset:swizzle(SWAP,1)
	v_mov_b32_e32 v6, 0
	v_mov_b32_e32 v7, 0
	s_waitcnt lgkmcnt(0)
	v_add_f32_e32 v4, v9, v4
	ds_swizzle_b32 v5, v4 offset:swizzle(SWAP,2)
	s_waitcnt lgkmcnt(0)
	v_add_f32_e32 v228, v4, v5
	ds_swizzle_b32 v229, v228 offset:swizzle(SWAP,4)
	v_mov_b32_e32 v4, 0
	v_mov_b32_e32 v5, 0
	s_and_saveexec_b64 s[30:31], s[8:9]
	s_cbranch_execz .LBB0_157
	ds_read_b128 v[4:7], v227 offset:33792
	v_add_u32_e32 v9, s82, v149
	ds_read_b128 v[10:13], v9 offset:51200
	s_waitcnt lgkmcnt(0)
	v_mfma_f32_16x16x32_bf16 v[4:7], v[4:7], v[10:13], 0
	ds_read_b128 v[10:13], v227 offset:33856
	ds_read_b128 v[14:17], v9 offset:51264
	s_waitcnt lgkmcnt(0)
	v_mfma_f32_16x16x32_bf16 v[4:7], v[10:13], v[14:17], v[4:7]
	ds_read_b128 v[10:13], v227 offset:33920
	ds_read_b128 v[14:17], v9 offset:51328
	s_waitcnt lgkmcnt(0)
	v_mfma_f32_16x16x32_bf16 v[4:7], v[10:13], v[14:17], v[4:7]
	ds_read_b128 v[10:13], v227 offset:33984
	ds_read_b128 v[14:17], v9 offset:51392
	s_waitcnt lgkmcnt(0)
	v_mfma_f32_16x16x32_bf16 v[4:7], v[10:13], v[14:17], v[4:7]
